# compact-grid-barrier-direct-generation-poll
# speedup vs baseline: 1.0165x; 1.0058x over previous
; __device__ __forceinline__ unsigned xb_ld(unsigned* p)              { return __hip_atomic_load(p, __ATOMIC_RELAXED, __HIP_MEMORY_SCOPE_AGENT); }
; __device__ __forceinline__ unsigned xb_add(unsigned* p, unsigned v) { return __hip_atomic_fetch_add(p, v, __ATOMIC_RELAXED, __HIP_MEMORY_SCOPE_AGENT); }
; #define XB_SPIN(cond, bar) do { unsigned _sp = 0; while (cond) { __builtin_amdgcn_s_sleep(1); \
;     if ((++_sp & 255u) == 0u) { if (xb_ld(&(bar)[XB_TMO])) break; if (_sp > XB_SPIN_CAP) { atomicAdd(&(bar)[XB_TMO], 1u); break; } } } } while (0)
; __device__ __forceinline__ void xcd_barrier(const XcdBarrier& b) {
;     asm volatile("s_waitcnt vmcnt(0)" ::: "memory");
;     __syncthreads();
;     if (threadIdx.x == 0) {
;         unsigned* bar = b.bar;
;         __builtin_amdgcn_s_waitcnt(0);
;         unsigned nloc = b.st[0], nx = b.st[1];
;         if (nloc == 0u) { xcd_barrier_complete(bar, b.x, nloc, nx); b.st[0] = nloc; b.st[1] = nx; }
;         const unsigned old = xb_add(&bar[XB_XSUB(b.x)], 1u);
;         const unsigned gen = old / nloc;
;         if (old + 1u == (gen + 1u) * nloc) {
;             __builtin_amdgcn_fence(__ATOMIC_RELEASE, "agent");
;             asm volatile("s_waitcnt vmcnt(0)" ::: "memory");
;             const unsigned og = xb_add(&bar[XB_TOP], 1u);
;             const unsigned tg = og / nx;
;             if (og + 1u == (tg + 1u) * nx) xb_add(&bar[XB_TOPGEN], 1u);
;             else XB_SPIN(xb_ld(&bar[XB_TOPGEN]) == tg, bar);
;             __builtin_amdgcn_fence(__ATOMIC_ACQUIRE, "agent");
;             xb_add(&bar[XB_XGEN(b.x)], 1u);
;             asm volatile("s_waitcnt vmcnt(0)" ::: "memory");
;         } else {
;             XB_SPIN(xb_ld(&bar[XB_XGEN(b.x)]) == gen, bar);
;             __builtin_amdgcn_fence(__ATOMIC_ACQUIRE, "agent");
;             asm volatile("s_waitcnt vmcnt(0)" ::: "memory");
;         }
;     }
;     __syncthreads();
; }
.LBB0_124:
	s_waitcnt vmcnt(0)
	s_barrier
	s_mov_b64 s[0:1], exec
	v_readlane_b32 s2, v254, 2
	v_readlane_b32 s3, v254, 3
	s_and_b64 s[2:3], s[0:1], s[2:3]
	s_mov_b64 exec, s[2:3]
	s_cbranch_execz .LBB0_176
	v_readlane_b32 s98, v254, 5
	v_readlane_b32 s99, v254, 6
	v_readlane_b32 s6, v254, 1
	v_mov_b32_e32 v0, 0x23fc0
	s_waitcnt vmcnt(0) lgkmcnt(0)
	ds_read2_b32 v[2:3], v0 offset1:1
	s_lshl_b32 s6, s6, 8
	s_add_u32 s100, s98, s6
	s_addc_u32 s101, s99, 0
	v_mov_b32_e32 v0, 0x1000
	v_mov_b32_e32 v1, 1
	global_atomic_add v4, v0, v1, s[100:101] offset:1024 sc0
	buffer_inv sc1
	s_waitcnt lgkmcnt(0)
	v_readfirstlane_b32 s2, v2
	v_readfirstlane_b32 s3, v3
	s_mul_i32 s2, s2, 2
	s_mul_i32 s3, s3, 2
	s_waitcnt vmcnt(1)
	v_readfirstlane_b32 s6, v4
	s_add_i32 s6, s6, 1
	s_cmp_lg_u32 s6, s2
	s_cbranch_scc1 .Lxb1_spin
	buffer_wbl2 sc1
	s_waitcnt vmcnt(0)
	v_mov_b32_e32 v0, 0x3000
	global_atomic_add v4, v0, v1, s[98:99] offset:1024 sc0
	s_waitcnt vmcnt(0)
	v_readfirstlane_b32 s6, v4
	s_add_i32 s6, s6, 1
	s_cmp_lg_u32 s6, s3
	s_cbranch_scc1 .Lxb1_spin
	v_mov_b32_e32 v0, 0x3100
	global_atomic_add v0, v1, s[98:99] offset:1024
	s_branch .Lxb1_done
.Lxb1_spin:
	v_mov_b32_e32 v0, 0x3100
	s_mov_b32 s7, 0x200000
.Lxb1_poll:
	global_load_dword v4, v0, s[98:99] offset:1024 sc1
	s_waitcnt vmcnt(0)
	v_readfirstlane_b32 s6, v4
	s_cmp_ge_u32 s6, 2
	s_cbranch_scc1 .Lxb1_done
	s_sleep 1
	s_add_i32 s7, s7, -1
	s_cmp_lg_u32 s7, 0
	s_cbranch_scc1 .Lxb1_poll
.Lxb1_done:
	s_waitcnt vmcnt(0)
.LBB0_176:
	s_or_b64 exec, exec, s[0:1]
	s_mov_b64 s[0:1], s[86:87]
	s_waitcnt lgkmcnt(0)
	v_mov_b32_e32 v0, v186
	s_barrier
	s_cmpk_lt_i32 s82, 0x540
	v_mov_b32_e32 v0, v186
	s_cselect_b64 s[2:3], -1, 0
	s_cmpk_gt_i32 s82, 0x53f
	v_readfirstlane_b32 s4, v0
	s_cbranch_scc0 .LBB0_179
	s_andn2_b64 vcc, exec, s[2:3]
	s_cbranch_vccz .LBB0_180

; __device__ __forceinline__ unsigned xb_ld(unsigned* p)              { return __hip_atomic_load(p, __ATOMIC_RELAXED, __HIP_MEMORY_SCOPE_AGENT); }
; __device__ __forceinline__ unsigned xb_add(unsigned* p, unsigned v) { return __hip_atomic_fetch_add(p, v, __ATOMIC_RELAXED, __HIP_MEMORY_SCOPE_AGENT); }
; #define XB_SPIN(cond, bar) do { unsigned _sp = 0; while (cond) { __builtin_amdgcn_s_sleep(1); \
;     if ((++_sp & 255u) == 0u) { if (xb_ld(&(bar)[XB_TMO])) break; if (_sp > XB_SPIN_CAP) { atomicAdd(&(bar)[XB_TMO], 1u); break; } } } } while (0)
; __device__ __forceinline__ void xcd_barrier(const XcdBarrier& b) {
;     asm volatile("s_waitcnt vmcnt(0)" ::: "memory");
;     __syncthreads();
;     if (threadIdx.x == 0) {
;         unsigned* bar = b.bar;
;         __builtin_amdgcn_s_waitcnt(0);
;         unsigned nloc = b.st[0], nx = b.st[1];
;         if (nloc == 0u) { xcd_barrier_complete(bar, b.x, nloc, nx); b.st[0] = nloc; b.st[1] = nx; }
;         const unsigned old = xb_add(&bar[XB_XSUB(b.x)], 1u);
;         const unsigned gen = old / nloc;
;         if (old + 1u == (gen + 1u) * nloc) {
;             __builtin_amdgcn_fence(__ATOMIC_RELEASE, "agent");
;             asm volatile("s_waitcnt vmcnt(0)" ::: "memory");
;             const unsigned og = xb_add(&bar[XB_TOP], 1u);
;             const unsigned tg = og / nx;
;             if (og + 1u == (tg + 1u) * nx) xb_add(&bar[XB_TOPGEN], 1u);
;             else XB_SPIN(xb_ld(&bar[XB_TOPGEN]) == tg, bar);
;             __builtin_amdgcn_fence(__ATOMIC_ACQUIRE, "agent");
;             xb_add(&bar[XB_XGEN(b.x)], 1u);
;             asm volatile("s_waitcnt vmcnt(0)" ::: "memory");
;         } else {
;             XB_SPIN(xb_ld(&bar[XB_XGEN(b.x)]) == gen, bar);
;             __builtin_amdgcn_fence(__ATOMIC_ACQUIRE, "agent");
;             asm volatile("s_waitcnt vmcnt(0)" ::: "memory");
;         }
;     }
;     __syncthreads();
; }
.LBB0_274:
	s_waitcnt vmcnt(0)
	s_waitcnt vmcnt(0)
	s_barrier
	s_mov_b64 s[0:1], exec
	v_readlane_b32 s2, v254, 2
	v_readlane_b32 s3, v254, 3
	s_and_b64 s[2:3], s[0:1], s[2:3]
	s_mov_b64 exec, s[2:3]
	s_cbranch_execz .LBB0_326
	v_readlane_b32 s98, v254, 5
	v_readlane_b32 s99, v254, 6
	v_readlane_b32 s6, v254, 1
	v_mov_b32_e32 v0, 0x23fc0
	s_waitcnt vmcnt(0) lgkmcnt(0)
	ds_read2_b32 v[2:3], v0 offset1:1
	s_lshl_b32 s6, s6, 8
	s_add_u32 s100, s98, s6
	s_addc_u32 s101, s99, 0
	v_mov_b32_e32 v0, 0x1000
	v_mov_b32_e32 v1, 1
	global_atomic_add v4, v0, v1, s[100:101] offset:1024 sc0
	buffer_inv sc1
	s_waitcnt lgkmcnt(0)
	v_readfirstlane_b32 s2, v2
	v_readfirstlane_b32 s3, v3
	s_mul_i32 s2, s2, 3
	s_mul_i32 s3, s3, 3
	s_waitcnt vmcnt(1)
	v_readfirstlane_b32 s6, v4
	s_add_i32 s6, s6, 1
	s_cmp_lg_u32 s6, s2
	s_cbranch_scc1 .Lxb2_spin
	buffer_wbl2 sc1
	s_waitcnt vmcnt(0)
	v_mov_b32_e32 v0, 0x3000
	global_atomic_add v4, v0, v1, s[98:99] offset:1024 sc0
	s_waitcnt vmcnt(0)
	v_readfirstlane_b32 s6, v4
	s_add_i32 s6, s6, 1
	s_cmp_lg_u32 s6, s3
	s_cbranch_scc1 .Lxb2_spin
	v_mov_b32_e32 v0, 0x3100
	global_atomic_add v0, v1, s[98:99] offset:1024
	s_branch .Lxb2_done

; __device__ __forceinline__ unsigned xb_ld(unsigned* p)              { return __hip_atomic_load(p, __ATOMIC_RELAXED, __HIP_MEMORY_SCOPE_AGENT); }
; __device__ __forceinline__ unsigned xb_add(unsigned* p, unsigned v) { return __hip_atomic_fetch_add(p, v, __ATOMIC_RELAXED, __HIP_MEMORY_SCOPE_AGENT); }
; #define XB_SPIN(cond, bar) do { unsigned _sp = 0; while (cond) { __builtin_amdgcn_s_sleep(1); \
;     if ((++_sp & 255u) == 0u) { if (xb_ld(&(bar)[XB_TMO])) break; if (_sp > XB_SPIN_CAP) { atomicAdd(&(bar)[XB_TMO], 1u); break; } } } } while (0)
; __device__ __forceinline__ void xcd_barrier(const XcdBarrier& b) {
;     ...
;             else XB_SPIN(xb_ld(&bar[XB_TOPGEN]) == tg, bar);
;             __builtin_amdgcn_fence(__ATOMIC_ACQUIRE, "agent");
;             xb_add(&bar[XB_XGEN(b.x)], 1u);
;             asm volatile("s_waitcnt vmcnt(0)" ::: "memory");
;         } else {
;             XB_SPIN(xb_ld(&bar[XB_XGEN(b.x)]) == gen, bar);
;     ...
;     const int per = (1536 + (int)gridDim.x - 1) / (int)gridDim.x, u0 = (int)blockIdx.x * per, u1 = (u0 + per < 1536) ? u0 + per : 1536;
;     int cur_half = 1;
;     for (int unit = u0; unit < u1; ++unit) {
.Lxb2_poll:
	global_load_dword v4, v0, s[98:99] offset:1024 sc1
	s_waitcnt vmcnt(0)
	v_readfirstlane_b32 s6, v4
	s_cmp_ge_u32 s6, 3
	s_cbranch_scc1 .Lxb2_done
	s_sleep 1
	s_add_i32 s7, s7, -1
	s_cmp_lg_u32 s7, 0
	s_cbranch_scc1 .Lxb2_poll
.Lxb2_done:
	s_waitcnt vmcnt(0)
.LBB0_326:
	s_or_b64 exec, exec, s[0:1]
	s_and_b32 s23, s82, 1
	s_add_i32 s0, s84, 0x5ff
	s_cmpk_lt_i32 s82, 0x200
	s_cselect_b64 s[2:3], -1, 0
	s_abs_i32 s1, s84
	s_waitcnt lgkmcnt(0)
	v_cvt_f32_u32_e32 v0, s1
	v_writelane_b32 v254, s2, 45
	v_mbcnt_hi_u32_b32 v187, -1, v148
	s_mov_b32 s39, 0
	v_rcp_iflag_f32_e32 v0, v0
	v_writelane_b32 v254, s3, 46
	s_sub_i32 s3, 0, s1
	s_xor_b32 s2, s0, s84
	v_mul_f32_e32 v0, 0x4f7ffffe, v0
	v_cvt_u32_f32_e32 v0, v0
	s_abs_i32 s0, s0
	s_ashr_i32 s2, s2, 31
	s_mov_b64 s[26:27], -1
	v_readfirstlane_b32 s4, v0
	s_mul_i32 s3, s3, s4
	s_mul_hi_u32 s3, s4, s3
	s_add_i32 s4, s4, s3
	s_mul_hi_u32 s3, s0, s4
	s_mul_i32 s4, s3, s1
	s_sub_i32 s0, s0, s4
	s_add_i32 s4, s3, 1
	s_sub_i32 s5, s0, s1
	s_cmp_ge_u32 s0, s1
	s_cselect_b32 s3, s4, s3
	s_cselect_b32 s0, s5, s0
	s_add_i32 s4, s3, 1
	s_cmp_ge_u32 s0, s1
	s_cselect_b32 s0, s4, s3
	s_xor_b32 s0, s0, s2
	s_sub_i32 s0, s0, s2
	s_mul_i32 s30, s0, s82
	s_add_i32 s0, s30, s0
	s_min_i32 s0, s0, 0x600
	s_cmp_lt_i32 s30, s0
	v_writelane_b32 v254, s0, 41
	s_cselect_b64 s[0:1], -1, 0
	s_lshl_b32 s2, s82, 7
	v_writelane_b32 v254, s2, 55
	s_lshl_b32 s2, s82, 5
	v_cndmask_b32_e64 v0, 0, 1, s[0:1]
	v_writelane_b32 v254, s2, 57
	v_cmp_ne_u32_e64 s[0:1], 1, v0
	s_lshl_b32 s22, s84, 7
	s_lshl_b32 s24, s84, 5
	v_writelane_b32 v254, s0, 53
	v_and_b32_e32 v0, 64, v187
	s_movk_i32 s34, 0x90
	v_writelane_b32 v254, s1, 54
	s_add_i32 s0, 0, 0x19800
	v_writelane_b32 v254, s0, 59
	v_writelane_b32 v254, s23, 47
	v_writelane_b32 v254, s22, 49
	v_mov_b32_e32 v3, 0
	s_movk_i32 s35, 0x2a00
	s_movk_i32 s29, 0x1000
	s_mov_b32 s31, 0x800000
	s_mov_b32 s36, 0x3f317217
	s_mov_b32 s37, 0x7f800000
	s_mov_b32 s4, 0xbfb8aa3b
	v_xor_b32_e32 v143, 16, v187
	v_add_u32_e32 v190, 64, v0
	v_xor_b32_e32 v142, 32, v187
	v_mov_b32_e32 v9, 0xff800000
	v_mov_b32_e32 v30, 0x41b17218
	v_mov_b32_e32 v31, 0x8800
	s_mov_b32 s0, 0
	v_writelane_b32 v254, s24, 51
	s_mov_b32 s28, 0xff800000
	s_barrier
	s_branch .LBB0_328

; __device__ __forceinline__ unsigned xb_ld(unsigned* p)              { return __hip_atomic_load(p, __ATOMIC_RELAXED, __HIP_MEMORY_SCOPE_AGENT); }
; __device__ __forceinline__ unsigned xb_add(unsigned* p, unsigned v) { return __hip_atomic_fetch_add(p, v, __ATOMIC_RELAXED, __HIP_MEMORY_SCOPE_AGENT); }
; #define XB_SPIN(cond, bar) do { unsigned _sp = 0; while (cond) { __builtin_amdgcn_s_sleep(1); \
;     if ((++_sp & 255u) == 0u) { if (xb_ld(&(bar)[XB_TMO])) break; if (_sp > XB_SPIN_CAP) { atomicAdd(&(bar)[XB_TMO], 1u); break; } } } } while (0)
; __device__ __forceinline__ void xcd_barrier(const XcdBarrier& b) {
;     asm volatile("s_waitcnt vmcnt(0)" ::: "memory");
;     __syncthreads();
;     if (threadIdx.x == 0) {
;         unsigned* bar = b.bar;
;         __builtin_amdgcn_s_waitcnt(0);
;         unsigned nloc = b.st[0], nx = b.st[1];
;         if (nloc == 0u) { xcd_barrier_complete(bar, b.x, nloc, nx); b.st[0] = nloc; b.st[1] = nx; }
;         const unsigned old = xb_add(&bar[XB_XSUB(b.x)], 1u);
;         const unsigned gen = old / nloc;
;         if (old + 1u == (gen + 1u) * nloc) {
;             __builtin_amdgcn_fence(__ATOMIC_RELEASE, "agent");
;             asm volatile("s_waitcnt vmcnt(0)" ::: "memory");
;             const unsigned og = xb_add(&bar[XB_TOP], 1u);
;             const unsigned tg = og / nx;
;             if (og + 1u == (tg + 1u) * nx) xb_add(&bar[XB_TOPGEN], 1u);
;             else XB_SPIN(xb_ld(&bar[XB_TOPGEN]) == tg, bar);
;             __builtin_amdgcn_fence(__ATOMIC_ACQUIRE, "agent");
;             xb_add(&bar[XB_XGEN(b.x)], 1u);
;             asm volatile("s_waitcnt vmcnt(0)" ::: "memory");
;         } else {
;             XB_SPIN(xb_ld(&bar[XB_XGEN(b.x)]) == gen, bar);
;             __builtin_amdgcn_fence(__ATOMIC_ACQUIRE, "agent");
;             asm volatile("s_waitcnt vmcnt(0)" ::: "memory");
;         }
;     }
;     __syncthreads();
; }
.LBB0_343:
	s_waitcnt vmcnt(0)
	s_barrier
	s_mov_b64 s[0:1], exec
	v_readlane_b32 s2, v254, 2
	v_readlane_b32 s3, v254, 3
	v_readlane_b32 s34, v254, 5
	s_and_b64 s[2:3], s[0:1], s[2:3]
	v_readlane_b32 s35, v254, 6
	v_readlane_b32 s36, v254, 17
	v_readlane_b32 s37, v254, 18
	s_mov_b64 exec, s[2:3]
	s_cbranch_execz .LBB0_395
	v_readlane_b32 s98, v254, 5
	v_readlane_b32 s99, v254, 6
	v_readlane_b32 s6, v254, 1
	v_mov_b32_e32 v0, 0x23fc0
	s_waitcnt vmcnt(0) lgkmcnt(0)
	ds_read2_b32 v[2:3], v0 offset1:1
	s_lshl_b32 s6, s6, 8
	s_add_u32 s100, s98, s6
	s_addc_u32 s101, s99, 0
	v_mov_b32_e32 v0, 0x1000
	v_mov_b32_e32 v1, 1
	global_atomic_add v4, v0, v1, s[100:101] offset:1024 sc0
	buffer_inv sc1
	s_waitcnt lgkmcnt(0)
	v_readfirstlane_b32 s2, v2
	v_readfirstlane_b32 s3, v3
	s_mul_i32 s2, s2, 4
	s_mul_i32 s3, s3, 4
	s_waitcnt vmcnt(1)
	v_readfirstlane_b32 s6, v4
	s_add_i32 s6, s6, 1
	s_cmp_lg_u32 s6, s2
	s_cbranch_scc1 .Lxb3_spin
	buffer_wbl2 sc1
	s_waitcnt vmcnt(0)
	v_mov_b32_e32 v0, 0x3000
	global_atomic_add v4, v0, v1, s[98:99] offset:1024 sc0
	s_waitcnt vmcnt(0)
	v_readfirstlane_b32 s6, v4
	s_add_i32 s6, s6, 1
	s_cmp_lg_u32 s6, s3
	s_cbranch_scc1 .Lxb3_spin
	v_mov_b32_e32 v0, 0x3100
	global_atomic_add v0, v1, s[98:99] offset:1024
	s_branch .Lxb3_done

; __device__ __forceinline__ unsigned xb_ld(unsigned* p)              { return __hip_atomic_load(p, __ATOMIC_RELAXED, __HIP_MEMORY_SCOPE_AGENT); }
; __device__ __forceinline__ unsigned xb_add(unsigned* p, unsigned v) { return __hip_atomic_fetch_add(p, v, __ATOMIC_RELAXED, __HIP_MEMORY_SCOPE_AGENT); }
; #define XB_SPIN(cond, bar) do { unsigned _sp = 0; while (cond) { __builtin_amdgcn_s_sleep(1); \
;     if ((++_sp & 255u) == 0u) { if (xb_ld(&(bar)[XB_TMO])) break; if (_sp > XB_SPIN_CAP) { atomicAdd(&(bar)[XB_TMO], 1u); break; } } } } while (0)
; #define X make_ctx(lds_raw)
; __device__ __forceinline__ void xcd_barrier(const XcdBarrier& b) {
;     ...
;             else XB_SPIN(xb_ld(&bar[XB_TOPGEN]) == tg, bar);
;             __builtin_amdgcn_fence(__ATOMIC_ACQUIRE, "agent");
;             xb_add(&bar[XB_XGEN(b.x)], 1u);
;             asm volatile("s_waitcnt vmcnt(0)" ::: "memory");
;         } else {
;             XB_SPIN(xb_ld(&bar[XB_XGEN(b.x)]) == gen, bar);
;     ...
;     for (int gid = X.gtid; gid < 131072; gid += X.nthr) {
.Lxb3_poll:
	global_load_dword v4, v0, s[98:99] offset:1024 sc1
	s_waitcnt vmcnt(0)
	v_readfirstlane_b32 s6, v4
	s_cmp_ge_u32 s6, 4
	s_cbranch_scc1 .Lxb3_done
	s_sleep 1
	s_add_i32 s7, s7, -1
	s_cmp_lg_u32 s7, 0
	s_cbranch_scc1 .Lxb3_poll
.Lxb3_done:
	s_waitcnt vmcnt(0)
.LBB0_395:
	s_or_b64 exec, exec, s[0:1]
	s_mov_b64 s[0:1], s[86:87]
	s_waitcnt lgkmcnt(0)
	v_mov_b32_e32 v0, v186
	v_readlane_b32 s2, v254, 4
	s_barrier
	s_nop 0
	v_add_u32_e32 v162, s2, v0
	s_mov_b32 s2, 0x20000
	v_cmp_gt_i32_e32 vcc, s2, v162
	s_and_saveexec_b64 s[8:9], vcc
	s_cbranch_execz .LBB0_398
	s_load_dwordx4 s[4:7], s[0:1], 0x98
	v_lshlrev_b32_e32 v0, 2, v0
	v_mov_b32_e32 v1, 0
	s_mov_b64 s[10:11], 0
	v_lshl_add_u32 v163, s82, 11, v0
	s_waitcnt lgkmcnt(0)
	s_add_u32 s6, s6, 0xc0000
	s_addc_u32 s7, s7, 0
	s_lshl_b32 s0, s84, 11
	v_mov_b32_e32 v166, v1
	v_mov_b32_e32 v167, v1
	s_movk_i32 s1, 0x2000
	s_movk_i32 s2, 0x3000
	s_mov_b32 s3, 0x1ffff

; __device__ __forceinline__ unsigned xb_ld(unsigned* p)              { return __hip_atomic_load(p, __ATOMIC_RELAXED, __HIP_MEMORY_SCOPE_AGENT); }
; __device__ __forceinline__ unsigned xb_add(unsigned* p, unsigned v) { return __hip_atomic_fetch_add(p, v, __ATOMIC_RELAXED, __HIP_MEMORY_SCOPE_AGENT); }
; #define XB_SPIN(cond, bar) do { unsigned _sp = 0; while (cond) { __builtin_amdgcn_s_sleep(1); \
;     if ((++_sp & 255u) == 0u) { if (xb_ld(&(bar)[XB_TMO])) break; if (_sp > XB_SPIN_CAP) { atomicAdd(&(bar)[XB_TMO], 1u); break; } } } } while (0)
; __device__ __forceinline__ void xcd_barrier(const XcdBarrier& b) {
;     asm volatile("s_waitcnt vmcnt(0)" ::: "memory");
;     __syncthreads();
;     if (threadIdx.x == 0) {
;         unsigned* bar = b.bar;
;         __builtin_amdgcn_s_waitcnt(0);
;         unsigned nloc = b.st[0], nx = b.st[1];
;         if (nloc == 0u) { xcd_barrier_complete(bar, b.x, nloc, nx); b.st[0] = nloc; b.st[1] = nx; }
;         const unsigned old = xb_add(&bar[XB_XSUB(b.x)], 1u);
;         const unsigned gen = old / nloc;
;         if (old + 1u == (gen + 1u) * nloc) {
;             __builtin_amdgcn_fence(__ATOMIC_RELEASE, "agent");
;             asm volatile("s_waitcnt vmcnt(0)" ::: "memory");
;             const unsigned og = xb_add(&bar[XB_TOP], 1u);
;             const unsigned tg = og / nx;
;             if (og + 1u == (tg + 1u) * nx) xb_add(&bar[XB_TOPGEN], 1u);
;             else XB_SPIN(xb_ld(&bar[XB_TOPGEN]) == tg, bar);
;             __builtin_amdgcn_fence(__ATOMIC_ACQUIRE, "agent");
;             xb_add(&bar[XB_XGEN(b.x)], 1u);
;             asm volatile("s_waitcnt vmcnt(0)" ::: "memory");
;         } else {
;             XB_SPIN(xb_ld(&bar[XB_XGEN(b.x)]) == gen, bar);
;             __builtin_amdgcn_fence(__ATOMIC_ACQUIRE, "agent");
;             asm volatile("s_waitcnt vmcnt(0)" ::: "memory");
;         }
;     }
;     __syncthreads();
; }
.LBB0_398:
	s_or_b64 exec, exec, s[8:9]
	s_waitcnt vmcnt(0)
	s_barrier
	s_mov_b64 s[0:1], exec
	v_readlane_b32 s2, v254, 2
	v_readlane_b32 s3, v254, 3
	s_and_b64 s[2:3], s[0:1], s[2:3]
	s_mov_b64 exec, s[2:3]
	s_cbranch_execz .LBB0_450
	v_readlane_b32 s98, v254, 5
	v_readlane_b32 s99, v254, 6
	v_readlane_b32 s6, v254, 1
	v_mov_b32_e32 v0, 0x23fc0
	s_waitcnt vmcnt(0) lgkmcnt(0)
	ds_read2_b32 v[2:3], v0 offset1:1
	s_lshl_b32 s6, s6, 8
	s_add_u32 s100, s98, s6
	s_addc_u32 s101, s99, 0
	v_mov_b32_e32 v0, 0x1000
	v_mov_b32_e32 v1, 1
	global_atomic_add v4, v0, v1, s[100:101] offset:1024 sc0
	buffer_inv sc1
	s_waitcnt lgkmcnt(0)
	v_readfirstlane_b32 s2, v2
	v_readfirstlane_b32 s3, v3
	s_mul_i32 s2, s2, 5
	s_mul_i32 s3, s3, 5
	s_waitcnt vmcnt(1)
	v_readfirstlane_b32 s6, v4
	s_add_i32 s6, s6, 1
	s_cmp_lg_u32 s6, s2
	s_cbranch_scc1 .Lxb4_spin
	buffer_wbl2 sc1
	s_waitcnt vmcnt(0)
	v_mov_b32_e32 v0, 0x3000
	global_atomic_add v4, v0, v1, s[98:99] offset:1024 sc0
	s_waitcnt vmcnt(0)
	v_readfirstlane_b32 s6, v4
	s_add_i32 s6, s6, 1
	s_cmp_lg_u32 s6, s3
	s_cbranch_scc1 .Lxb4_spin
	v_mov_b32_e32 v0, 0x3100
	global_atomic_add v0, v1, s[98:99] offset:1024
	s_branch .Lxb4_done

; __device__ __forceinline__ unsigned xb_ld(unsigned* p)              { return __hip_atomic_load(p, __ATOMIC_RELAXED, __HIP_MEMORY_SCOPE_AGENT); }
; __device__ __forceinline__ unsigned xb_add(unsigned* p, unsigned v) { return __hip_atomic_fetch_add(p, v, __ATOMIC_RELAXED, __HIP_MEMORY_SCOPE_AGENT); }
; #define XB_SPIN(cond, bar) do { unsigned _sp = 0; while (cond) { __builtin_amdgcn_s_sleep(1); \
;     if ((++_sp & 255u) == 0u) { if (xb_ld(&(bar)[XB_TMO])) break; if (_sp > XB_SPIN_CAP) { atomicAdd(&(bar)[XB_TMO], 1u); break; } } } } while (0)
; __device__ __forceinline__ KArgs kargs() { KArgs p = (KArgs)__builtin_amdgcn_kernarg_segment_ptr(); asm volatile("" : "+s"(p)); return p; }
; __device__ __forceinline__ void xcd_barrier(const XcdBarrier& b) {
;     ...
;             else XB_SPIN(xb_ld(&bar[XB_TOPGEN]) == tg, bar);
;             __builtin_amdgcn_fence(__ATOMIC_ACQUIRE, "agent");
;             xb_add(&bar[XB_XGEN(b.x)], 1u);
;             asm volatile("s_waitcnt vmcnt(0)" ::: "memory");
;         } else {
;             XB_SPIN(xb_ld(&bar[XB_XGEN(b.x)]) == gen, bar);
; __global__ void __launch_bounds__(512, 2) fwd_megakernel(Args a_kernarg) {
;     ...
;     if ((blockIdx.x & 1) == 0) { KArgs a = kargs(); pg8::Gemm g{WSP(bf16_t, WS_HBUF), WSP(bf16_t, WS_WMAB), NT, NGATE, DM, DM, DM};
.Lxb4_poll:
	global_load_dword v4, v0, s[98:99] offset:1024 sc1
	s_waitcnt vmcnt(0)
	v_readfirstlane_b32 s6, v4
	s_cmp_ge_u32 s6, 5
	s_cbranch_scc1 .Lxb4_done
	s_sleep 1
	s_add_i32 s7, s7, -1
	s_cmp_lg_u32 s7, 0
	s_cbranch_scc1 .Lxb4_poll
.Lxb4_done:
	s_waitcnt vmcnt(0)
.LBB0_450:
	s_or_b64 exec, exec, s[0:1]
	v_readlane_b32 s0, v254, 45
	v_readlane_b32 s1, v254, 46
	s_cmp_lg_u32 s23, 0
	s_cselect_b64 s[20:21], -1, 0
	s_waitcnt lgkmcnt(0)
	v_cndmask_b32_e64 v0, 0, 1, s[0:1]
	s_cmp_eq_u32 s23, 0
	v_cmp_ne_u32_e64 s[4:5], 1, v0
	s_barrier
	s_cbranch_scc0 .LBB0_475
	s_mov_b64 s[2:3], s[86:87]
	v_mov_b32_e32 v0, v186
	s_and_b64 vcc, exec, s[4:5]
	v_mov_b32_e32 v0, v186
	s_nop 0
	v_readfirstlane_b32 s16, v0
	s_cbranch_vccnz .LBB0_475
	s_ashr_i32 s18, s82, 31
	s_load_dwordx2 s[0:1], s[2:3], 0xa0
	s_lshr_b32 s6, s18, 29
	s_add_i32 s9, s82, s6
	s_and_b32 s6, s9, -8
	s_sub_i32 s10, s82, s6
	s_cmp_gt_i32 s10, -1
	s_cbranch_scc0 .LBB0_454
	s_lshl_b32 s8, s10, 6
	s_load_dwordx2 s[2:3], s[2:3], 0x98
	s_cbranch_execz .LBB0_455
	s_branch .LBB0_456

; __device__ __forceinline__ unsigned xb_ld(unsigned* p)              { return __hip_atomic_load(p, __ATOMIC_RELAXED, __HIP_MEMORY_SCOPE_AGENT); }
; __device__ __forceinline__ unsigned xb_add(unsigned* p, unsigned v) { return __hip_atomic_fetch_add(p, v, __ATOMIC_RELAXED, __HIP_MEMORY_SCOPE_AGENT); }
; #define XB_SPIN(cond, bar) do { unsigned _sp = 0; while (cond) { __builtin_amdgcn_s_sleep(1); \
;     if ((++_sp & 255u) == 0u) { if (xb_ld(&(bar)[XB_TMO])) break; if (_sp > XB_SPIN_CAP) { atomicAdd(&(bar)[XB_TMO], 1u); break; } } } } while (0)
; __device__ __forceinline__ void xcd_barrier(const XcdBarrier& b) {
;     asm volatile("s_waitcnt vmcnt(0)" ::: "memory");
;     __syncthreads();
;     if (threadIdx.x == 0) {
;         unsigned* bar = b.bar;
;         __builtin_amdgcn_s_waitcnt(0);
;         unsigned nloc = b.st[0], nx = b.st[1];
;         if (nloc == 0u) { xcd_barrier_complete(bar, b.x, nloc, nx); b.st[0] = nloc; b.st[1] = nx; }
;         const unsigned old = xb_add(&bar[XB_XSUB(b.x)], 1u);
;         const unsigned gen = old / nloc;
;         if (old + 1u == (gen + 1u) * nloc) {
;             __builtin_amdgcn_fence(__ATOMIC_RELEASE, "agent");
;             asm volatile("s_waitcnt vmcnt(0)" ::: "memory");
;             const unsigned og = xb_add(&bar[XB_TOP], 1u);
;             const unsigned tg = og / nx;
;             if (og + 1u == (tg + 1u) * nx) xb_add(&bar[XB_TOPGEN], 1u);
;             else XB_SPIN(xb_ld(&bar[XB_TOPGEN]) == tg, bar);
;             __builtin_amdgcn_fence(__ATOMIC_ACQUIRE, "agent");
;             xb_add(&bar[XB_XGEN(b.x)], 1u);
;             asm volatile("s_waitcnt vmcnt(0)" ::: "memory");
;         } else {
;             XB_SPIN(xb_ld(&bar[XB_XGEN(b.x)]) == gen, bar);
;             __builtin_amdgcn_fence(__ATOMIC_ACQUIRE, "agent");
;             asm volatile("s_waitcnt vmcnt(0)" ::: "memory");
;         }
;     }
;     __syncthreads();
; }
.LBB0_530:
	s_waitcnt vmcnt(0)
	s_waitcnt vmcnt(0)
	s_barrier
	s_mov_b64 s[0:1], exec
	v_readlane_b32 s2, v254, 2
	v_readlane_b32 s3, v254, 3
	s_and_b64 s[2:3], s[0:1], s[2:3]
	s_mov_b64 exec, s[2:3]
	s_cbranch_execz .LBB0_582
	v_readlane_b32 s98, v254, 5
	v_readlane_b32 s99, v254, 6
	v_readlane_b32 s6, v254, 1
	v_mov_b32_e32 v0, 0x23fc0
	s_waitcnt vmcnt(0) lgkmcnt(0)
	ds_read2_b32 v[2:3], v0 offset1:1
	s_lshl_b32 s6, s6, 8
	s_add_u32 s100, s98, s6
	s_addc_u32 s101, s99, 0
	v_mov_b32_e32 v0, 0x1000
	v_mov_b32_e32 v1, 1
	global_atomic_add v4, v0, v1, s[100:101] offset:1024 sc0
	buffer_inv sc1
	s_waitcnt lgkmcnt(0)
	v_readfirstlane_b32 s2, v2
	v_readfirstlane_b32 s3, v3
	s_mul_i32 s2, s2, 6
	s_mul_i32 s3, s3, 6
	s_waitcnt vmcnt(1)
	v_readfirstlane_b32 s6, v4
	s_add_i32 s6, s6, 1
	s_cmp_lg_u32 s6, s2
	s_cbranch_scc1 .Lxb5_spin
	buffer_wbl2 sc1
	s_waitcnt vmcnt(0)
	v_mov_b32_e32 v0, 0x3000
	global_atomic_add v4, v0, v1, s[98:99] offset:1024 sc0
	s_waitcnt vmcnt(0)
	v_readfirstlane_b32 s6, v4
	s_add_i32 s6, s6, 1
	s_cmp_lg_u32 s6, s3
	s_cbranch_scc1 .Lxb5_spin
	v_mov_b32_e32 v0, 0x3100
	global_atomic_add v0, v1, s[98:99] offset:1024
	s_branch .Lxb5_done

; __device__ __forceinline__ unsigned xb_ld(unsigned* p)              { return __hip_atomic_load(p, __ATOMIC_RELAXED, __HIP_MEMORY_SCOPE_AGENT); }
; __device__ __forceinline__ unsigned xb_add(unsigned* p, unsigned v) { return __hip_atomic_fetch_add(p, v, __ATOMIC_RELAXED, __HIP_MEMORY_SCOPE_AGENT); }
; #define XB_SPIN(cond, bar) do { unsigned _sp = 0; while (cond) { __builtin_amdgcn_s_sleep(1); \
;     if ((++_sp & 255u) == 0u) { if (xb_ld(&(bar)[XB_TMO])) break; if (_sp > XB_SPIN_CAP) { atomicAdd(&(bar)[XB_TMO], 1u); break; } } } } while (0)
;     __host__ __device__ bool next(int i, Unit& u) const {
;         const long L = (long)i * G + c; if (L >= nwg) return false;
;         int wgid = (int)L; { const int q = nwg / NXCD, r = nwg % NXCD, xcd = wgid % NXCD, off = wgid / NXCD; wgid = (xcd < r ? xcd * (q + 1) : r * (q + 1) + (xcd - r) * q) + off; }
;         const int nig = WGM * nN, gid = wgid / nig, fm = gid * WGM, gsz = (nM - fm) < WGM ? (nM - fm) : WGM;
;         u.pm = fm + ((wgid % nig) % gsz); u.pn = (wgid % nig) / gsz; return true;
; __device__ __forceinline__ void xcd_barrier(const XcdBarrier& b) {
;     ...
;             else XB_SPIN(xb_ld(&bar[XB_TOPGEN]) == tg, bar);
;             __builtin_amdgcn_fence(__ATOMIC_ACQUIRE, "agent");
;             xb_add(&bar[XB_XGEN(b.x)], 1u);
;             asm volatile("s_waitcnt vmcnt(0)" ::: "memory");
;         } else {
;             XB_SPIN(xb_ld(&bar[XB_XGEN(b.x)]) == gen, bar);
.Lxb5_poll:
	global_load_dword v4, v0, s[98:99] offset:1024 sc1
	s_waitcnt vmcnt(0)
	v_readfirstlane_b32 s6, v4
	s_cmp_ge_u32 s6, 6
	s_cbranch_scc1 .Lxb5_done
	s_sleep 1
	s_add_i32 s7, s7, -1
	s_cmp_lg_u32 s7, 0
	s_cbranch_scc1 .Lxb5_poll
.Lxb5_done:
	s_waitcnt vmcnt(0)
.LBB0_582:
	s_or_b64 exec, exec, s[0:1]
	s_mov_b64 s[0:1], s[86:87]
	s_waitcnt lgkmcnt(0)
	v_mov_b32_e32 v0, v186
	v_readlane_b32 s2, v254, 12
	s_barrier
	v_readlane_b32 s3, v254, 13
	v_mov_b32_e32 v0, v186
	s_andn2_b64 vcc, exec, s[2:3]
	v_cndmask_b32_e64 v1, 0, 1, s[2:3]
	v_cmp_ne_u32_e64 s[4:5], 1, v1
	v_readfirstlane_b32 s6, v0
	s_cbranch_vccnz .LBB0_606
	s_ashr_i32 s22, s82, 31
	s_lshr_b32 s2, s22, 29
	s_add_i32 s12, s82, s2
	s_and_b32 s2, s12, -8
	s_sub_i32 s13, s82, s2
	s_cmp_gt_i32 s13, -1
	s_cbranch_scc0 .LBB0_585
	s_lshl_b32 s7, s13, 5
	s_load_dwordx4 s[8:11], s[0:1], 0x98
	s_cbranch_execz .LBB0_586
	s_branch .LBB0_587

; __device__ __forceinline__ unsigned xb_ld(unsigned* p)              { return __hip_atomic_load(p, __ATOMIC_RELAXED, __HIP_MEMORY_SCOPE_AGENT); }
; __device__ __forceinline__ unsigned xb_add(unsigned* p, unsigned v) { return __hip_atomic_fetch_add(p, v, __ATOMIC_RELAXED, __HIP_MEMORY_SCOPE_AGENT); }
; #define XB_SPIN(cond, bar) do { unsigned _sp = 0; while (cond) { __builtin_amdgcn_s_sleep(1); \
;     if ((++_sp & 255u) == 0u) { if (xb_ld(&(bar)[XB_TMO])) break; if (_sp > XB_SPIN_CAP) { atomicAdd(&(bar)[XB_TMO], 1u); break; } } } } while (0)
; __device__ __forceinline__ void xcd_barrier(const XcdBarrier& b) {
;     asm volatile("s_waitcnt vmcnt(0)" ::: "memory");
;     __syncthreads();
;     if (threadIdx.x == 0) {
;         unsigned* bar = b.bar;
;         __builtin_amdgcn_s_waitcnt(0);
;         unsigned nloc = b.st[0], nx = b.st[1];
;         if (nloc == 0u) { xcd_barrier_complete(bar, b.x, nloc, nx); b.st[0] = nloc; b.st[1] = nx; }
;         const unsigned old = xb_add(&bar[XB_XSUB(b.x)], 1u);
;         const unsigned gen = old / nloc;
;         if (old + 1u == (gen + 1u) * nloc) {
;             __builtin_amdgcn_fence(__ATOMIC_RELEASE, "agent");
;             asm volatile("s_waitcnt vmcnt(0)" ::: "memory");
;             const unsigned og = xb_add(&bar[XB_TOP], 1u);
;             const unsigned tg = og / nx;
;             if (og + 1u == (tg + 1u) * nx) xb_add(&bar[XB_TOPGEN], 1u);
;             else XB_SPIN(xb_ld(&bar[XB_TOPGEN]) == tg, bar);
;             __builtin_amdgcn_fence(__ATOMIC_ACQUIRE, "agent");
;             xb_add(&bar[XB_XGEN(b.x)], 1u);
;             asm volatile("s_waitcnt vmcnt(0)" ::: "memory");
;         } else {
;             XB_SPIN(xb_ld(&bar[XB_XGEN(b.x)]) == gen, bar);
;             __builtin_amdgcn_fence(__ATOMIC_ACQUIRE, "agent");
;             asm volatile("s_waitcnt vmcnt(0)" ::: "memory");
;         }
;     }
;     __syncthreads();
; }
.LBB0_606:
	s_waitcnt vmcnt(0)
	s_barrier
	s_mov_b64 s[0:1], exec
	v_readlane_b32 s2, v254, 2
	v_readlane_b32 s3, v254, 3
	s_and_b64 s[2:3], s[0:1], s[2:3]
	s_mov_b64 exec, s[2:3]
	s_cbranch_execz .LBB0_658
	v_readlane_b32 s98, v254, 5
	v_readlane_b32 s99, v254, 6
	v_readlane_b32 s6, v254, 1
	v_mov_b32_e32 v0, 0x23fc0
	s_waitcnt vmcnt(0) lgkmcnt(0)
	ds_read2_b32 v[2:3], v0 offset1:1
	s_lshl_b32 s6, s6, 8
	s_add_u32 s100, s98, s6
	s_addc_u32 s101, s99, 0
	v_mov_b32_e32 v0, 0x1000
	v_mov_b32_e32 v1, 1
	global_atomic_add v4, v0, v1, s[100:101] offset:1024 sc0
	buffer_inv sc1
	s_waitcnt lgkmcnt(0)
	v_readfirstlane_b32 s2, v2
	v_readfirstlane_b32 s3, v3
	s_mul_i32 s2, s2, 7
	s_mul_i32 s3, s3, 7
	s_waitcnt vmcnt(1)
	v_readfirstlane_b32 s6, v4
	s_add_i32 s6, s6, 1
	s_cmp_lg_u32 s6, s2
	s_cbranch_scc1 .Lxb6_spin
	buffer_wbl2 sc1
	s_waitcnt vmcnt(0)
	v_mov_b32_e32 v0, 0x3000
	global_atomic_add v4, v0, v1, s[98:99] offset:1024 sc0
	s_waitcnt vmcnt(0)
	v_readfirstlane_b32 s6, v4
	s_add_i32 s6, s6, 1
	s_cmp_lg_u32 s6, s3
	s_cbranch_scc1 .Lxb6_spin
	v_mov_b32_e32 v0, 0x3100
	global_atomic_add v0, v1, s[98:99] offset:1024
	s_branch .Lxb6_done

; __device__ __forceinline__ unsigned xb_ld(unsigned* p)              { return __hip_atomic_load(p, __ATOMIC_RELAXED, __HIP_MEMORY_SCOPE_AGENT); }
; __device__ __forceinline__ unsigned xb_add(unsigned* p, unsigned v) { return __hip_atomic_fetch_add(p, v, __ATOMIC_RELAXED, __HIP_MEMORY_SCOPE_AGENT); }
; #define XB_SPIN(cond, bar) do { unsigned _sp = 0; while (cond) { __builtin_amdgcn_s_sleep(1); \
;     if ((++_sp & 255u) == 0u) { if (xb_ld(&(bar)[XB_TMO])) break; if (_sp > XB_SPIN_CAP) { atomicAdd(&(bar)[XB_TMO], 1u); break; } } } } while (0)
;     __host__ __device__ bool next(int i, Unit& u) const {
;         const long L = (long)i * G + c; if (L >= nwg) return false;
;         int wgid = (int)L; { const int q = nwg / NXCD, r = nwg % NXCD, xcd = wgid % NXCD, off = wgid / NXCD; wgid = (xcd < r ? xcd * (q + 1) : r * (q + 1) + (xcd - r) * q) + off; }
;         const int nig = WGM * nN, gid = wgid / nig, fm = gid * WGM, gsz = (nM - fm) < WGM ? (nM - fm) : WGM;
;         u.pm = fm + ((wgid % nig) % gsz); u.pn = (wgid % nig) / gsz; return true;
; __device__ __forceinline__ void xcd_barrier(const XcdBarrier& b) {
;     ...
;             else XB_SPIN(xb_ld(&bar[XB_TOPGEN]) == tg, bar);
;             __builtin_amdgcn_fence(__ATOMIC_ACQUIRE, "agent");
;             xb_add(&bar[XB_XGEN(b.x)], 1u);
;             asm volatile("s_waitcnt vmcnt(0)" ::: "memory");
;         } else {
;             XB_SPIN(xb_ld(&bar[XB_XGEN(b.x)]) == gen, bar);
.Lxb6_poll:
	global_load_dword v4, v0, s[98:99] offset:1024 sc1
	s_waitcnt vmcnt(0)
	v_readfirstlane_b32 s6, v4
	s_cmp_ge_u32 s6, 7
	s_cbranch_scc1 .Lxb6_done
	s_sleep 1
	s_add_i32 s7, s7, -1
	s_cmp_lg_u32 s7, 0
	s_cbranch_scc1 .Lxb6_poll
.Lxb6_done:
	s_waitcnt vmcnt(0)
.LBB0_658:
	s_or_b64 exec, exec, s[0:1]
	s_mov_b64 s[0:1], s[86:87]
	s_waitcnt lgkmcnt(0)
	v_mov_b32_e32 v0, v186
	v_mov_b32_e32 v183, v186
	s_barrier
	s_and_b64 vcc, exec, s[4:5]
	v_readfirstlane_b32 s20, v183
	s_cbranch_vccnz .LBB0_709
	s_ashr_i32 s23, s82, 31
	s_load_dwordx2 s[12:13], s[0:1], 0xa0
	s_lshr_b32 s2, s23, 29
	s_add_i32 s7, s82, s2
	s_and_b32 s2, s7, -8
	s_sub_i32 s8, s82, s2
	s_cmp_gt_i32 s8, -1
	s_cbranch_scc0 .LBB0_661
	s_lshl_b32 s6, s8, 5
	s_cbranch_execz .LBB0_662
	s_branch .LBB0_663

; __device__ __forceinline__ unsigned xb_ld(unsigned* p)              { return __hip_atomic_load(p, __ATOMIC_RELAXED, __HIP_MEMORY_SCOPE_AGENT); }
; __device__ __forceinline__ unsigned xb_add(unsigned* p, unsigned v) { return __hip_atomic_fetch_add(p, v, __ATOMIC_RELAXED, __HIP_MEMORY_SCOPE_AGENT); }
; #define XB_SPIN(cond, bar) do { unsigned _sp = 0; while (cond) { __builtin_amdgcn_s_sleep(1); \
;     if ((++_sp & 255u) == 0u) { if (xb_ld(&(bar)[XB_TMO])) break; if (_sp > XB_SPIN_CAP) { atomicAdd(&(bar)[XB_TMO], 1u); break; } } } } while (0)
; __device__ __forceinline__ void xcd_barrier(const XcdBarrier& b) {
;     asm volatile("s_waitcnt vmcnt(0)" ::: "memory");
;     __syncthreads();
;     if (threadIdx.x == 0) {
;         unsigned* bar = b.bar;
;         __builtin_amdgcn_s_waitcnt(0);
;         unsigned nloc = b.st[0], nx = b.st[1];
;         if (nloc == 0u) { xcd_barrier_complete(bar, b.x, nloc, nx); b.st[0] = nloc; b.st[1] = nx; }
;         const unsigned old = xb_add(&bar[XB_XSUB(b.x)], 1u);
;         const unsigned gen = old / nloc;
;         if (old + 1u == (gen + 1u) * nloc) {
;             __builtin_amdgcn_fence(__ATOMIC_RELEASE, "agent");
;             asm volatile("s_waitcnt vmcnt(0)" ::: "memory");
;             const unsigned og = xb_add(&bar[XB_TOP], 1u);
;             const unsigned tg = og / nx;
;             if (og + 1u == (tg + 1u) * nx) xb_add(&bar[XB_TOPGEN], 1u);
;             else XB_SPIN(xb_ld(&bar[XB_TOPGEN]) == tg, bar);
;             __builtin_amdgcn_fence(__ATOMIC_ACQUIRE, "agent");
;             xb_add(&bar[XB_XGEN(b.x)], 1u);
;             asm volatile("s_waitcnt vmcnt(0)" ::: "memory");
;         } else {
;             XB_SPIN(xb_ld(&bar[XB_XGEN(b.x)]) == gen, bar);
;             __builtin_amdgcn_fence(__ATOMIC_ACQUIRE, "agent");
;             asm volatile("s_waitcnt vmcnt(0)" ::: "memory");
;         }
;     }
;     __syncthreads();
; }
.LBB0_709:
	s_waitcnt vmcnt(0)
	s_barrier
	s_mov_b64 s[0:1], exec
	v_readlane_b32 s2, v254, 2
	v_readlane_b32 s3, v254, 3
	s_and_b64 s[2:3], s[0:1], s[2:3]
	s_mov_b64 exec, s[2:3]
	s_cbranch_execz .LBB0_761
	v_readlane_b32 s98, v254, 5
	v_readlane_b32 s99, v254, 6
	v_readlane_b32 s6, v254, 1
	v_mov_b32_e32 v0, 0x23fc0
	s_waitcnt vmcnt(0) lgkmcnt(0)
	ds_read2_b32 v[2:3], v0 offset1:1
	s_lshl_b32 s6, s6, 8
	s_add_u32 s100, s98, s6
	s_addc_u32 s101, s99, 0
	v_mov_b32_e32 v0, 0x1000
	v_mov_b32_e32 v1, 1
	global_atomic_add v4, v0, v1, s[100:101] offset:1024 sc0
	buffer_inv sc1
	s_waitcnt lgkmcnt(0)
	v_readfirstlane_b32 s2, v2
	v_readfirstlane_b32 s3, v3
	s_mul_i32 s2, s2, 8
	s_mul_i32 s3, s3, 8
	s_waitcnt vmcnt(1)
	v_readfirstlane_b32 s6, v4
	s_add_i32 s6, s6, 1
	s_cmp_lg_u32 s6, s2
	s_cbranch_scc1 .Lxb7_spin
	buffer_wbl2 sc1
	s_waitcnt vmcnt(0)
	v_mov_b32_e32 v0, 0x3000
	global_atomic_add v4, v0, v1, s[98:99] offset:1024 sc0
	s_waitcnt vmcnt(0)
	v_readfirstlane_b32 s6, v4
	s_add_i32 s6, s6, 1
	s_cmp_lg_u32 s6, s3
	s_cbranch_scc1 .Lxb7_spin
	v_mov_b32_e32 v0, 0x3100
	global_atomic_add v0, v1, s[98:99] offset:1024
	s_branch .Lxb7_done

; __device__ __forceinline__ unsigned xb_ld(unsigned* p)              { return __hip_atomic_load(p, __ATOMIC_RELAXED, __HIP_MEMORY_SCOPE_AGENT); }
; __device__ __forceinline__ unsigned xb_add(unsigned* p, unsigned v) { return __hip_atomic_fetch_add(p, v, __ATOMIC_RELAXED, __HIP_MEMORY_SCOPE_AGENT); }
; #define XB_SPIN(cond, bar) do { unsigned _sp = 0; while (cond) { __builtin_amdgcn_s_sleep(1); \
;     if ((++_sp & 255u) == 0u) { if (xb_ld(&(bar)[XB_TMO])) break; if (_sp > XB_SPIN_CAP) { atomicAdd(&(bar)[XB_TMO], 1u); break; } } } } while (0)
;     __host__ __device__ bool next(int i, Unit& u) const {
;         const long L = (long)i * G + c; if (L >= nwg) return false;
;         int wgid = (int)L; { const int q = nwg / NXCD, r = nwg % NXCD, xcd = wgid % NXCD, off = wgid / NXCD; wgid = (xcd < r ? xcd * (q + 1) : r * (q + 1) + (xcd - r) * q) + off; }
;         const int nig = WGM * nN, gid = wgid / nig, fm = gid * WGM, gsz = (nM - fm) < WGM ? (nM - fm) : WGM;
;         u.pm = fm + ((wgid % nig) % gsz); u.pn = (wgid % nig) / gsz; return true;
; __device__ __forceinline__ void xcd_barrier(const XcdBarrier& b) {
;     ...
;             else XB_SPIN(xb_ld(&bar[XB_TOPGEN]) == tg, bar);
;             __builtin_amdgcn_fence(__ATOMIC_ACQUIRE, "agent");
;             xb_add(&bar[XB_XGEN(b.x)], 1u);
;             asm volatile("s_waitcnt vmcnt(0)" ::: "memory");
;         } else {
;             XB_SPIN(xb_ld(&bar[XB_XGEN(b.x)]) == gen, bar);
.Lxb7_poll:
	global_load_dword v4, v0, s[98:99] offset:1024 sc1
	s_waitcnt vmcnt(0)
	v_readfirstlane_b32 s6, v4
	s_cmp_ge_u32 s6, 8
	s_cbranch_scc1 .Lxb7_done
	s_sleep 1
	s_add_i32 s7, s7, -1
	s_cmp_lg_u32 s7, 0
	s_cbranch_scc1 .Lxb7_poll
.Lxb7_done:
	s_waitcnt vmcnt(0)
.LBB0_761:
	s_or_b64 exec, exec, s[0:1]
	s_mov_b64 s[2:3], s[86:87]
	s_waitcnt lgkmcnt(0)
	s_barrier
	s_load_dwordx2 s[0:1], s[2:3], 0xa0
	v_mov_b32_e32 v0, v186
	s_cmpk_lt_i32 s82, 0x5ac
	v_mov_b32_e32 v0, v186
	s_cselect_b64 s[6:7], -1, 0
	s_cmpk_gt_i32 s82, 0x5ab
	v_readfirstlane_b32 s11, v0
	s_cbranch_scc1 .LBB0_767
	s_ashr_i32 s8, s82, 31
	s_lshr_b32 s8, s8, 29
	s_add_i32 s10, s82, s8
	s_and_b32 s8, s10, -8
	s_sub_i32 s12, s82, s8
	s_cmp_gt_i32 s12, 3
	s_cbranch_scc0 .LBB0_764
	s_mul_i32 s8, s12, 0xb5
	s_add_i32 s13, s8, 4
	s_cbranch_execz .LBB0_765
	s_branch .LBB0_766

; __device__ __forceinline__ unsigned xb_ld(unsigned* p)              { return __hip_atomic_load(p, __ATOMIC_RELAXED, __HIP_MEMORY_SCOPE_AGENT); }
; __device__ __forceinline__ unsigned xb_add(unsigned* p, unsigned v) { return __hip_atomic_fetch_add(p, v, __ATOMIC_RELAXED, __HIP_MEMORY_SCOPE_AGENT); }
; #define XB_SPIN(cond, bar) do { unsigned _sp = 0; while (cond) { __builtin_amdgcn_s_sleep(1); \
;     if ((++_sp & 255u) == 0u) { if (xb_ld(&(bar)[XB_TMO])) break; if (_sp > XB_SPIN_CAP) { atomicAdd(&(bar)[XB_TMO], 1u); break; } } } } while (0)
; __device__ __forceinline__ void xcd_barrier(const XcdBarrier& b) {
;     asm volatile("s_waitcnt vmcnt(0)" ::: "memory");
;     __syncthreads();
;     if (threadIdx.x == 0) {
;         unsigned* bar = b.bar;
;         __builtin_amdgcn_s_waitcnt(0);
;         unsigned nloc = b.st[0], nx = b.st[1];
;         if (nloc == 0u) { xcd_barrier_complete(bar, b.x, nloc, nx); b.st[0] = nloc; b.st[1] = nx; }
;         const unsigned old = xb_add(&bar[XB_XSUB(b.x)], 1u);
;         const unsigned gen = old / nloc;
;         if (old + 1u == (gen + 1u) * nloc) {
;             __builtin_amdgcn_fence(__ATOMIC_RELEASE, "agent");
;             asm volatile("s_waitcnt vmcnt(0)" ::: "memory");
;             const unsigned og = xb_add(&bar[XB_TOP], 1u);
;             const unsigned tg = og / nx;
;             if (og + 1u == (tg + 1u) * nx) xb_add(&bar[XB_TOPGEN], 1u);
;             else XB_SPIN(xb_ld(&bar[XB_TOPGEN]) == tg, bar);
;             __builtin_amdgcn_fence(__ATOMIC_ACQUIRE, "agent");
;             xb_add(&bar[XB_XGEN(b.x)], 1u);
;             asm volatile("s_waitcnt vmcnt(0)" ::: "memory");
;         } else {
;             XB_SPIN(xb_ld(&bar[XB_XGEN(b.x)]) == gen, bar);
;             __builtin_amdgcn_fence(__ATOMIC_ACQUIRE, "agent");
;             asm volatile("s_waitcnt vmcnt(0)" ::: "memory");
;         }
;     }
;     __syncthreads();
; }
.LBB0_856:
	s_waitcnt vmcnt(0)
	s_waitcnt vmcnt(0) lgkmcnt(0)
	s_barrier
	s_mov_b64 s[0:1], exec
	v_readlane_b32 s2, v254, 2
	v_readlane_b32 s3, v254, 3
	s_and_b64 s[2:3], s[0:1], s[2:3]
	s_mov_b64 exec, s[2:3]
	s_cbranch_execz .LBB0_908
	v_readlane_b32 s98, v254, 5
	v_readlane_b32 s99, v254, 6
	v_readlane_b32 s6, v254, 1
	v_mov_b32_e32 v0, 0x23fc0
	s_waitcnt vmcnt(0) lgkmcnt(0)
	ds_read2_b32 v[2:3], v0 offset1:1
	s_lshl_b32 s6, s6, 8
	s_add_u32 s100, s98, s6
	s_addc_u32 s101, s99, 0
	v_mov_b32_e32 v0, 0x1000
	v_mov_b32_e32 v1, 1
	global_atomic_add v4, v0, v1, s[100:101] offset:1024 sc0
	buffer_inv sc1
	s_waitcnt lgkmcnt(0)
	v_readfirstlane_b32 s2, v2
	v_readfirstlane_b32 s3, v3
	s_mul_i32 s2, s2, 9
	s_mul_i32 s3, s3, 9
	s_waitcnt vmcnt(1)
	v_readfirstlane_b32 s6, v4
	s_add_i32 s6, s6, 1
	s_cmp_lg_u32 s6, s2
	s_cbranch_scc1 .Lxb8_spin
	buffer_wbl2 sc1
	s_waitcnt vmcnt(0)
	v_mov_b32_e32 v0, 0x3000
	global_atomic_add v4, v0, v1, s[98:99] offset:1024 sc0
	s_waitcnt vmcnt(0)
	v_readfirstlane_b32 s6, v4
	s_add_i32 s6, s6, 1
	s_cmp_lg_u32 s6, s3
	s_cbranch_scc1 .Lxb8_spin
	v_mov_b32_e32 v0, 0x3100
	global_atomic_add v0, v1, s[98:99] offset:1024
	s_branch .Lxb8_done

; __device__ __forceinline__ unsigned xb_ld(unsigned* p)              { return __hip_atomic_load(p, __ATOMIC_RELAXED, __HIP_MEMORY_SCOPE_AGENT); }
; __device__ __forceinline__ unsigned xb_add(unsigned* p, unsigned v) { return __hip_atomic_fetch_add(p, v, __ATOMIC_RELAXED, __HIP_MEMORY_SCOPE_AGENT); }
; #define XB_SPIN(cond, bar) do { unsigned _sp = 0; while (cond) { __builtin_amdgcn_s_sleep(1); \
;     if ((++_sp & 255u) == 0u) { if (xb_ld(&(bar)[XB_TMO])) break; if (_sp > XB_SPIN_CAP) { atomicAdd(&(bar)[XB_TMO], 1u); break; } } } } while (0)
;     __host__ __device__ bool next(int i, Unit& u) const {
;         const long L = (long)i * G + c; if (L >= nwg) return false;
;         int wgid = (int)L; { const int q = nwg / NXCD, r = nwg % NXCD, xcd = wgid % NXCD, off = wgid / NXCD; wgid = (xcd < r ? xcd * (q + 1) : r * (q + 1) + (xcd - r) * q) + off; }
;         const int nig = WGM * nN, gid = wgid / nig, fm = gid * WGM, gsz = (nM - fm) < WGM ? (nM - fm) : WGM;
;         u.pm = fm + ((wgid % nig) % gsz); u.pn = (wgid % nig) / gsz; return true;
; __device__ __forceinline__ void xcd_barrier(const XcdBarrier& b) {
;     ...
;             else XB_SPIN(xb_ld(&bar[XB_TOPGEN]) == tg, bar);
;             __builtin_amdgcn_fence(__ATOMIC_ACQUIRE, "agent");
;             xb_add(&bar[XB_XGEN(b.x)], 1u);
;             asm volatile("s_waitcnt vmcnt(0)" ::: "memory");
;         } else {
;             XB_SPIN(xb_ld(&bar[XB_XGEN(b.x)]) == gen, bar);
.Lxb8_poll:
	global_load_dword v4, v0, s[98:99] offset:1024 sc1
	s_waitcnt vmcnt(0)
	v_readfirstlane_b32 s6, v4
	s_cmp_ge_u32 s6, 9
	s_cbranch_scc1 .Lxb8_done
	s_sleep 1
	s_add_i32 s7, s7, -1
	s_cmp_lg_u32 s7, 0
	s_cbranch_scc1 .Lxb8_poll
.Lxb8_done:
	s_waitcnt vmcnt(0)
.LBB0_908:
	s_or_b64 exec, exec, s[0:1]
	s_waitcnt lgkmcnt(0)
	v_mov_b32_e32 v0, v186
	s_barrier
	s_and_b64 vcc, exec, s[4:5]
	v_readfirstlane_b32 s18, v186
	s_cbranch_vccnz .LBB0_959
	s_ashr_i32 s21, s82, 31
	s_load_dwordx4 s[8:11], s[86:87], 0x90
	s_load_dwordx2 s[6:7], s[86:87], 0xa0
	s_lshr_b32 s0, s21, 29
	s_add_i32 s3, s82, s0
	s_and_b32 s0, s3, -8
	s_sub_i32 s2, s82, s0
	s_cmp_gt_i32 s2, -1
	s_cbranch_scc0 .LBB0_911
	s_lshl_b32 s4, s2, 5
	s_ashr_i32 s0, s3, 3
	s_cbranch_execz .LBB0_912
	s_branch .LBB0_913

; #define LAS __attribute__((address_space(3)))
; #define X make_ctx(lds_raw)
; __global__ void __launch_bounds__(512, 2) fwd_megakernel(Args a_kernarg) {
;     extern __shared__ __attribute__((aligned(16))) unsigned char lds_raw[];
;     cg::grid_group grid = cg::this_grid();
;     ...
;     { volatile LAS unsigned* st0 = (volatile LAS unsigned*)((LAS unsigned char*)lds_raw + LDS_BYTES - 64); if (threadIdx.x < 2) st0[threadIdx.x] = 0u; }
;     __syncthreads();
;     const XcdBarrier xbar = xcd_barrier_post((unsigned*)(kargs()->ws), (volatile LAS unsigned*)((LAS unsigned char*)lds_raw + LDS_BYTES - 64));
;     ...
;     phase0(X, kargs());
;     if (gridDim.x == 0x7fffffffu) grid.sync();
;     xcd_barrier(xbar);
;     { KArgs a = kargs(); norm_pass<0>(X, a, a->x, WSP(bf16_t, WS_HBUF), nullptr); }
;     __syncthreads();
;     phase0_transposes(X, kargs(), 0, 16 * 96 + 16 * 72 + 16 * 64, X.gw, X.ngw);
;     xcd_barrier(xbar);
;     { KArgs a = kargs(); pg8::Gemm g{WSP(bf16_t, WS_HBUF), WSP(bf16_t, WS_WMAIN), NT, NMAIN, DM, DM, DM}; run_gemm<0>(X, g, FStoreProj{WSP(bf16_t, WS_BIG), WSP(f32x2, WS_ROPE)}); }
;     { const int nfull = (gridDim.x > 64) ? 64 : 0;
;       if ((int)blockIdx.x >= nfull) phase0_transposes(X, kargs(), 16 * 96 + 16 * 72 + 16 * 64, -1, ((int)blockIdx.x - nfull) * 8 + X.wave, ((int)gridDim.x - nfull) * 8); }
;     xcd_barrier(xbar);
; #pragma unroll 1
;     for (int step = 0; step < 2; ++step) {
;         if (((step ^ (int)blockIdx.x) & 1) == 0) { KArgs a = kargs(); gla_a1(X, a, a->out, WSP(float, WS_SSQ)); }
;         else attn_mfma(X, kargs());
;         __syncthreads();
;     }
;     xcd_barrier(xbar);
;     { KArgs a = kargs(); gla_a2(X, a, a->out, WSP(float, WS_SSQ)); }
;     xcd_barrier(xbar);
;     if ((blockIdx.x & 1) == 0) { KArgs a = kargs(); pg8::Gemm g{WSP(bf16_t, WS_HBUF), WSP(bf16_t, WS_WMAB), NT, NGATE, DM, DM, DM};
;         run_gemm<1>(X, g, FSigmoidSplit{(bf16_t*)a->out + (size_t)NT * DM, WSP(bf16_t, WS_BIG) + C_AK}); }
;     __syncthreads();
;     { KArgs a = kargs(); gla_a3(X, a, a->out); }
;     attn_combine(X, kargs());
;     __syncthreads();
;     if ((blockIdx.x & 1) != 0) { KArgs a = kargs(); pg8::Gemm g{WSP(bf16_t, WS_HBUF), WSP(bf16_t, WS_WMAB), NT, NGATE, DM, DM, DM};
;         run_gemm<1>(X, g, FSigmoidSplit{(bf16_t*)a->out + (size_t)NT * DM, WSP(bf16_t, WS_BIG) + C_AK}); }
;     xcd_barrier(xbar);
	.amdhsa_kernel _Z14fwd_megakernel4Args
		.amdhsa_group_segment_fixed_size 0
		.amdhsa_private_segment_fixed_size 0
		.amdhsa_kernarg_size 424
		.amdhsa_user_sgpr_count 2
		.amdhsa_user_sgpr_dispatch_ptr 0
		.amdhsa_user_sgpr_queue_ptr 0
		.amdhsa_user_sgpr_kernarg_segment_ptr 1
		.amdhsa_user_sgpr_dispatch_id 0
		.amdhsa_user_sgpr_kernarg_preload_length 0
		.amdhsa_user_sgpr_kernarg_preload_offset 0
		.amdhsa_user_sgpr_private_segment_size 0
		.amdhsa_uses_dynamic_stack 0
		.amdhsa_enable_private_segment 0
		.amdhsa_system_sgpr_workgroup_id_x 1
		.amdhsa_system_sgpr_workgroup_id_y 0
		.amdhsa_system_sgpr_workgroup_id_z 0
		.amdhsa_system_sgpr_workgroup_info 0
		.amdhsa_system_vgpr_workitem_id 2
		.amdhsa_next_free_vgpr 256
		.amdhsa_next_free_sgpr 102
		.amdhsa_accum_offset 256
		.amdhsa_reserve_vcc 1
		.amdhsa_float_round_mode_32 0
		.amdhsa_float_round_mode_16_64 0
		.amdhsa_float_denorm_mode_32 3
		.amdhsa_float_denorm_mode_16_64 3
		.amdhsa_dx10_clamp 1
		.amdhsa_ieee_mode 1
		.amdhsa_fp16_overflow 0
		.amdhsa_tg_split 0
		.amdhsa_exception_fp_ieee_invalid_op 0
		.amdhsa_exception_fp_denorm_src 0
		.amdhsa_exception_fp_ieee_div_zero 0
		.amdhsa_exception_fp_ieee_overflow 0
		.amdhsa_exception_fp_ieee_underflow 0
		.amdhsa_exception_fp_ieee_inexact 0
		.amdhsa_exception_int_div_zero 0
	.end_amdhsa_kernel

; #define LAS __attribute__((address_space(3)))
; #define X make_ctx(lds_raw)
; __global__ void __launch_bounds__(512, 2) fwd_megakernel(Args a_kernarg) {
;     extern __shared__ __attribute__((aligned(16))) unsigned char lds_raw[];
;     cg::grid_group grid = cg::this_grid();
;     ...
;     { volatile LAS unsigned* st0 = (volatile LAS unsigned*)((LAS unsigned char*)lds_raw + LDS_BYTES - 64); if (threadIdx.x < 2) st0[threadIdx.x] = 0u; }
;     __syncthreads();
;     const XcdBarrier xbar = xcd_barrier_post((unsigned*)(kargs()->ws), (volatile LAS unsigned*)((LAS unsigned char*)lds_raw + LDS_BYTES - 64));
;     ...
;     phase0(X, kargs());
;     if (gridDim.x == 0x7fffffffu) grid.sync();
;     xcd_barrier(xbar);
;     { KArgs a = kargs(); norm_pass<0>(X, a, a->x, WSP(bf16_t, WS_HBUF), nullptr); }
;     __syncthreads();
;     phase0_transposes(X, kargs(), 0, 16 * 96 + 16 * 72 + 16 * 64, X.gw, X.ngw);
;     xcd_barrier(xbar);
;     { KArgs a = kargs(); pg8::Gemm g{WSP(bf16_t, WS_HBUF), WSP(bf16_t, WS_WMAIN), NT, NMAIN, DM, DM, DM}; run_gemm<0>(X, g, FStoreProj{WSP(bf16_t, WS_BIG), WSP(f32x2, WS_ROPE)}); }
;     { const int nfull = (gridDim.x > 64) ? 64 : 0;
;       if ((int)blockIdx.x >= nfull) phase0_transposes(X, kargs(), 16 * 96 + 16 * 72 + 16 * 64, -1, ((int)blockIdx.x - nfull) * 8 + X.wave, ((int)gridDim.x - nfull) * 8); }
;     xcd_barrier(xbar);
; #pragma unroll 1
;     for (int step = 0; step < 2; ++step) {
;         if (((step ^ (int)blockIdx.x) & 1) == 0) { KArgs a = kargs(); gla_a1(X, a, a->out, WSP(float, WS_SSQ)); }
;         else attn_mfma(X, kargs());
;         __syncthreads();
;     }
;     xcd_barrier(xbar);
;     { KArgs a = kargs(); gla_a2(X, a, a->out, WSP(float, WS_SSQ)); }
;     xcd_barrier(xbar);
;     if ((blockIdx.x & 1) == 0) { KArgs a = kargs(); pg8::Gemm g{WSP(bf16_t, WS_HBUF), WSP(bf16_t, WS_WMAB), NT, NGATE, DM, DM, DM};
;         run_gemm<1>(X, g, FSigmoidSplit{(bf16_t*)a->out + (size_t)NT * DM, WSP(bf16_t, WS_BIG) + C_AK}); }
;     __syncthreads();
;     { KArgs a = kargs(); gla_a3(X, a, a->out); }
;     attn_combine(X, kargs());
;     __syncthreads();
;     if ((blockIdx.x & 1) != 0) { KArgs a = kargs(); pg8::Gemm g{WSP(bf16_t, WS_HBUF), WSP(bf16_t, WS_WMAB), NT, NGATE, DM, DM, DM};
;         run_gemm<1>(X, g, FSigmoidSplit{(bf16_t*)a->out + (size_t)NT * DM, WSP(bf16_t, WS_BIG) + C_AK}); }
;     xcd_barrier(xbar);
amdhsa.kernels:
  - .agpr_count:     0
    .args:
      - .offset:         0
        .size:           168
        .value_kind:     by_value
      - .offset:         168
        .size:           4
        .value_kind:     hidden_block_count_x
      - .offset:         172
        .size:           4
        .value_kind:     hidden_block_count_y
      - .offset:         176
        .size:           4
        .value_kind:     hidden_block_count_z
      - .offset:         180
        .size:           2
        .value_kind:     hidden_group_size_x
      - .offset:         182
        .size:           2
        .value_kind:     hidden_group_size_y
      - .offset:         184
        .size:           2
        .value_kind:     hidden_group_size_z
      - .offset:         186
        .size:           2
        .value_kind:     hidden_remainder_x
      - .offset:         188
        .size:           2
        .value_kind:     hidden_remainder_y
      - .offset:         190
        .size:           2
        .value_kind:     hidden_remainder_z
      - .offset:         208
        .size:           8
        .value_kind:     hidden_global_offset_x
      - .offset:         216
        .size:           8
        .value_kind:     hidden_global_offset_y
      - .offset:         224
        .size:           8
        .value_kind:     hidden_global_offset_z
      - .offset:         232
        .size:           2
        .value_kind:     hidden_grid_dims
      - .offset:         256
        .size:           8
        .value_kind:     hidden_multigrid_sync_arg
      - .offset:         288
        .size:           4
        .value_kind:     hidden_dynamic_lds_size
    .group_segment_fixed_size: 0
    .kernarg_segment_align: 8
    .kernarg_segment_size: 424
    .language:       OpenCL C
    .language_version:
      - 2
      - 0
    .max_flat_workgroup_size: 512
    .name:           _Z14fwd_megakernel4Args
    .private_segment_fixed_size: 0
    .sgpr_count:     108
    .sgpr_spill_count: 93
    .symbol:         _Z14fwd_megakernel4Args.kd
    .uniform_work_group_size: 1
    .uses_dynamic_stack: false
    .vgpr_count:     256
    .vgpr_spill_count: 0
    .wavefront_size: 64
